# cross-attention units run on the CU that produced their q_mem tile, so the P10 to P11 grid barrier becomes a workgroup barrier plus L1 invalidate
# baseline (speedup 1.0000x reference)
; __device__ __forceinline__ unsigned xb_ld(unsigned* p)              { return __hip_atomic_load(p, __ATOMIC_RELAXED, __HIP_MEMORY_SCOPE_AGENT); }
; __device__ __forceinline__ unsigned xb_add(unsigned* p, unsigned v) { return __hip_atomic_fetch_add(p, v, __ATOMIC_RELAXED, __HIP_MEMORY_SCOPE_AGENT); }
; #define XB_SPIN(cond, bar) do { unsigned _sp = 0; while (cond) { __builtin_amdgcn_s_sleep(1); \
;     if ((++_sp & 255u) == 0u) { if (xb_ld(&(bar)[XB_TMO])) break; if (_sp > XB_SPIN_CAP) { atomicAdd(&(bar)[XB_TMO], 1u); break; } } } } while (0)
; __device__ __forceinline__ void xcd_barrier(const XcdBarrier& b) {
;     asm volatile("s_waitcnt vmcnt(0)" ::: "memory");
;     __syncthreads();
;     if (threadIdx.x == 0) {
;         unsigned* bar = b.bar;
;         __builtin_amdgcn_s_waitcnt(0);
;         unsigned nloc = b.st[0], nx = b.st[1];
;         if (nloc == 0u) { xcd_barrier_complete(bar, b.x, nloc, nx); b.st[0] = nloc; b.st[1] = nx; }
;         const unsigned old = xb_add(&bar[XB_XSUB(b.x)], 1u);
;         const unsigned gen = old / nloc;
;         if (old + 1u == (gen + 1u) * nloc) {
;             __builtin_amdgcn_fence(__ATOMIC_RELEASE, "agent");
;             asm volatile("s_waitcnt vmcnt(0)" ::: "memory");
;             const unsigned og = xb_add(&bar[XB_TOP], 1u);
;             const unsigned tg = og / nx;
;             if (og + 1u == (tg + 1u) * nx) xb_add(&bar[XB_TOPGEN], 1u);
;             else XB_SPIN(xb_ld(&bar[XB_TOPGEN]) == tg, bar);
;             __builtin_amdgcn_fence(__ATOMIC_ACQUIRE, "agent");
;             xb_add(&bar[XB_XGEN(b.x)], 1u);
;             asm volatile("s_waitcnt vmcnt(0)" ::: "memory");
;         } else {
;             XB_SPIN(xb_ld(&bar[XB_XGEN(b.x)]) == gen, bar);
;             __builtin_amdgcn_fence(__ATOMIC_ACQUIRE, "agent");
;             asm volatile("s_waitcnt vmcnt(0)" ::: "memory");
;         }
;     }
;     __syncthreads();
; }
.LBB0_786:
	s_cmp_gt_i32 s11, 11
	s_cselect_b64 s[0:1], -1, 0
	s_and_b64 s[2:3], s[4:5], s[0:1]
	s_andn2_b64 vcc, exec, s[2:3]
	s_cbranch_vccnz .LBB0_840
	s_waitcnt vmcnt(0)
	s_waitcnt vmcnt(0) lgkmcnt(0)
	s_barrier
	buffer_inv sc1
	s_waitcnt vmcnt(0)
	s_branch .LBB0_840
	s_add_i32 s4, 0, 0x20000
	v_mov_b32_e32 v0, s4
	s_waitcnt vmcnt(0) expcnt(0) lgkmcnt(0)
	ds_read_b32 v2, v0
	s_add_i32 s4, 0, 0x20004
	v_mov_b32_e32 v0, s4
	ds_read_b32 v0, v0
	s_waitcnt lgkmcnt(1)
	v_cmp_ne_u32_e32 vcc, 0, v2
	s_cbranch_vccnz .LBB0_803
	s_load_dwordx2 s[14:15], s[92:93], 0x4
	s_add_u32 s4, s26, 0x1000
	s_addc_u32 s5, s27, 0
	s_add_u32 s12, s26, 0x1100
	s_addc_u32 s13, s27, 0
	s_waitcnt lgkmcnt(0)
	s_mul_i32 s28, s14, s9
	s_add_u32 s14, s26, 0x1200
	s_mul_i32 s28, s28, s15
	s_addc_u32 s15, s27, 0
	s_add_u32 s16, s26, 0x1300
	s_addc_u32 s17, s27, 0
	s_mov_b32 s29, 1
	v_mov_b32_e32 v16, 0
	s_branch .LBB0_791

; __device__ __forceinline__ int crow(int r, int hi) { return (r & 3) + 8 * (r >> 2) + 4 * hi; }
;     ...
;   if (hi == 0) li_l[r32] = l_reg; asm volatile("s_waitcnt lgkmcnt(0)" ::: "memory");
;   if constexpr (MODE == 1) { if (hi == 0) lse_out[(long)(wid * QBLK + r32) * lse_stride] = m_reg * SCALE + __logf(l_reg); }
;   float rli[16];
; #pragma unroll
;   for (int r = 0; r < 16; ++r) rli[r] = __builtin_amdgcn_rcpf(li_l[crow(r, hi)]);
;   bf16* Ow = Ob + (long)(wid * QBLK) * ldo;
; #pragma unroll
;   for (int r = 0; r < 16; ++r) { const int orow = crow(r, hi);
; #pragma unroll
;     for (int d0 = 0; d0 < 4; ++d0) Ow[(long)orow * ldo + d0 * 32 + r32] = __float2bfloat16(o[d0][r] * rli[r]); }
; __global__ void __launch_bounds__(NWAVES * 64, 2) mk_fwd(Args args) {
;     ...
;     if (IN(11)) {
;         for (int u = vcu; u < 512; u += G) {
;             const int qb = u >> 2, h = u & 3; const size_t rowq = (size_t)qb * 256; const int b = (int)(rowq / SEQ);
;             const att::bf16* kv = (const att::bf16*)KVM + (size_t)b * MEMT * (2 * MEMW);
;             att::attn_unit<0>((const att::bf16*)QM + rowq * MEMW + h * 128, MEMW, kv + h * 128, kv + MEMW + h * 128, 2 * MEMW,
;                               (att::bf16*)OM + rowq * MEMW + h * 128, MEMW, MEMT / 64, (char*)lds, 0, 0, nullptr, nullptr, 0);
.LBB0_840:
	s_cmp_lt_i32 s10, 12
	s_cselect_b64 s[2:3], -1, 0
	s_and_b64 s[12:13], s[2:3], s[0:1]
	s_xor_b64 s[0:1], s[12:13], -1
	s_cmpk_gt_i32 s70, 0x1ff
	s_cselect_b64 s[2:3], -1, 0
	s_or_b64 s[0:1], s[0:1], s[2:3]
	s_and_b64 vcc, exec, s[0:1]
	s_cbranch_vccnz .LBB0_859
	s_add_u32 s18, s26, 0xc100000
	s_addc_u32 s19, s27, 0
	s_add_u32 s20, s26, 0x14800000
	s_addc_u32 s21, s27, 0
	s_add_u32 s30, s26, 0x16800000
	s_addc_u32 s31, s27, 0
	s_lshr_b32 s34, s70, 4
	s_lshl_b32 s34, s34, 5
	s_and_b32 s35, s70, 7
	s_lshl_b32 s35, s35, 2
	s_add_i32 s34, s34, s35
	s_bfe_u32 s35, s70, 0x10003
	s_lshl_b32 s35, s35, 1
	s_add_i32 s70, s34, s35
	s_lshl_b32 s34, s70, 7
	s_movk_i32 s35, 0x80
	s_waitcnt lgkmcnt(0)
	s_movk_i32 s36, 0xffe0
	v_mov_b32_e32 v161, 0
	s_movk_i32 s37, 0x2000
	s_mov_b32 s38, 0x10000
	s_add_i32 s39, 0, 0x10000
	s_mov_b32 s40, 0x20000
	s_mov_b32 s41, 0x30000
	s_add_i32 s42, 0, 0x14000
	s_mov_b32 s43, 0x42b504f3
	v_mov_b32_e32 v162, 0xf149f2ca
	s_mov_b32 s44, 0x40000
	s_mov_b32 s45, 0x50000
	s_mov_b32 s46, 0x60000
	s_mov_b32 s47, 0x70000
	s_movk_i32 s48, 0x4000
	s_movk_i32 s49, 0x6000
	s_branch .LBB0_843
.LBB0_842:
	s_or_b64 exec, exec, s[4:5]
	s_waitcnt lgkmcnt(0)
	v_add_u32_e32 v72, s28, v160
	ds_read_b128 v[64:67], v72
	ds_read_b128 v[68:71], v72 offset:32
	s_lshl_b64 s[2:3], s[14:15], 1
	s_add_u32 s1, s30, s2
	s_addc_u32 s2, s31, s3
	s_add_u32 s3, s1, s50
	s_waitcnt lgkmcnt(1)
	v_rcp_f32_e32 v73, v64
	v_rcp_f32_e32 v74, v65
	v_rcp_f32_e32 v75, v66
	v_rcp_f32_e32 v76, v67
	ds_read_b128 v[64:67], v72 offset:64
	s_addc_u32 s2, s2, 0
	s_ashr_i32 s1, s0, 31
	s_lshl_b64 s[0:1], s[0:1], 10
	s_add_u32 s0, s3, s0
	s_addc_u32 s1, s2, s1
	v_lshlrev_b32_e32 v160, 1, v164
	s_waitcnt lgkmcnt(1)
	v_rcp_f32_e32 v77, v68
	v_rcp_f32_e32 v78, v69
	v_rcp_f32_e32 v79, v70
	v_rcp_f32_e32 v80, v71
	ds_read_b128 v[68:71], v72 offset:96
	s_waitcnt lgkmcnt(1)
	v_rcp_f32_e32 v72, v64
	v_rcp_f32_e32 v81, v65
	v_rcp_f32_e32 v82, v66
	v_rcp_f32_e32 v83, v67
	v_lshlrev_b32_e32 v64, 12, v163
	v_lshl_add_u64 v[66:67], s[0:1], 0, v[160:161]
	v_mov_b32_e32 v65, v161
	v_mul_f32_e32 v0, v0, v73
	v_lshl_add_u64 v[64:65], v[66:67], 0, v[64:65]
	v_cvt_pk_bf16_f32 v0, v0, s0
	global_store_short v[64:65], v0, off
	v_mul_f32_e32 v0, v16, v73
	v_cvt_pk_bf16_f32 v0, v0, s0
	global_store_short v[64:65], v0, off offset:64
	v_mul_f32_e32 v0, v32, v73
	v_cvt_pk_bf16_f32 v0, v0, s0
	global_store_short v[64:65], v0, off offset:128
	v_mul_f32_e32 v0, v48, v73
	v_cvt_pk_bf16_f32 v0, v0, s0
	global_store_short v[64:65], v0, off offset:192
	v_mul_f32_e32 v0, v1, v74
	v_cvt_pk_bf16_f32 v0, v0, s0
	global_store_short v[64:65], v0, off offset:1024
	v_mul_f32_e32 v0, v17, v74
	v_cvt_pk_bf16_f32 v0, v0, s0
	global_store_short v[64:65], v0, off offset:1088
	v_mul_f32_e32 v0, v33, v74
	v_cvt_pk_bf16_f32 v0, v0, s0
	global_store_short v[64:65], v0, off offset:1152
	v_mul_f32_e32 v0, v49, v74
	v_cvt_pk_bf16_f32 v0, v0, s0
	global_store_short v[64:65], v0, off offset:1216
	v_mul_f32_e32 v0, v2, v75
	v_cvt_pk_bf16_f32 v0, v0, s0
	global_store_short v[64:65], v0, off offset:2048
	v_mul_f32_e32 v0, v18, v75
	v_cvt_pk_bf16_f32 v0, v0, s0
	global_store_short v[64:65], v0, off offset:2112
	v_mul_f32_e32 v0, v34, v75
	v_cvt_pk_bf16_f32 v0, v0, s0
	global_store_short v[64:65], v0, off offset:2176
	v_mul_f32_e32 v0, v50, v75
	v_cvt_pk_bf16_f32 v0, v0, s0
	global_store_short v[64:65], v0, off offset:2240
	v_mul_f32_e32 v0, v3, v76
	v_cvt_pk_bf16_f32 v0, v0, s0
	global_store_short v[64:65], v0, off offset:3072
	v_mul_f32_e32 v0, v19, v76
	v_cvt_pk_bf16_f32 v0, v0, s0
	global_store_short v[64:65], v0, off offset:3136
	v_mul_f32_e32 v0, v35, v76
	v_cvt_pk_bf16_f32 v0, v0, s0
	global_store_short v[64:65], v0, off offset:3200
	v_mul_f32_e32 v0, v51, v76
	v_cvt_pk_bf16_f32 v0, v0, s0
	global_store_short v[64:65], v0, off offset:3264
	v_mul_f32_e32 v0, v4, v77
	v_cvt_pk_bf16_f32 v2, v0, s0
	v_add_co_u32_e32 v0, vcc, s37, v64
	s_waitcnt lgkmcnt(0)
; __device__ __forceinline__ int crow(int r, int hi) { return (r & 3) + 8 * (r >> 2) + 4 * hi; }
;     ...
;   bf16* Ow = Ob + (long)(wid * QBLK) * ldo;
; #pragma unroll
;   for (int r = 0; r < 16; ++r) { const int orow = crow(r, hi);
; #pragma unroll
;     for (int d0 = 0; d0 < 4; ++d0) Ow[(long)orow * ldo + d0 * 32 + r32] = __float2bfloat16(o[d0][r] * rli[r]); }
; __global__ void __launch_bounds__(NWAVES * 64, 2) mk_fwd(Args args) {
;     ...
;         for (int u = vcu; u < 512; u += G) {
;             const int qb = u >> 2, h = u & 3; const size_t rowq = (size_t)qb * 256; const int b = (int)(rowq / SEQ);
	v_rcp_f32_e32 v68, v68
	v_addc_co_u32_e32 v1, vcc, 0, v65, vcc
	global_store_short v[0:1], v2, off
	v_mul_f32_e32 v2, v20, v77
	v_cvt_pk_bf16_f32 v2, v2, s0
	global_store_short v[0:1], v2, off offset:64
	v_mul_f32_e32 v2, v36, v77
	v_cvt_pk_bf16_f32 v2, v2, s0
	global_store_short v[0:1], v2, off offset:128
	v_mul_f32_e32 v2, v52, v77
	v_cvt_pk_bf16_f32 v2, v2, s0
	global_store_short v[0:1], v2, off offset:192
	v_mul_f32_e32 v2, v5, v78
	v_cvt_pk_bf16_f32 v2, v2, s0
	global_store_short v[0:1], v2, off offset:1024
	v_mul_f32_e32 v2, v21, v78
	v_cvt_pk_bf16_f32 v2, v2, s0
	global_store_short v[0:1], v2, off offset:1088
	v_mul_f32_e32 v2, v37, v78
	v_cvt_pk_bf16_f32 v2, v2, s0
	global_store_short v[0:1], v2, off offset:1152
	v_mul_f32_e32 v2, v53, v78
	v_cvt_pk_bf16_f32 v2, v2, s0
	global_store_short v[0:1], v2, off offset:1216
	v_mul_f32_e32 v2, v6, v79
	v_cvt_pk_bf16_f32 v2, v2, s0
	global_store_short v[0:1], v2, off offset:2048
	v_mul_f32_e32 v2, v22, v79
	v_cvt_pk_bf16_f32 v2, v2, s0
	global_store_short v[0:1], v2, off offset:2112
	v_mul_f32_e32 v2, v38, v79
	v_cvt_pk_bf16_f32 v2, v2, s0
	global_store_short v[0:1], v2, off offset:2176
	v_mul_f32_e32 v2, v54, v79
	v_cvt_pk_bf16_f32 v2, v2, s0
	global_store_short v[0:1], v2, off offset:2240
	v_mul_f32_e32 v2, v7, v80
	v_cvt_pk_bf16_f32 v2, v2, s0
	global_store_short v[0:1], v2, off offset:3072
	v_mul_f32_e32 v2, v23, v80
	v_cvt_pk_bf16_f32 v2, v2, s0
	global_store_short v[0:1], v2, off offset:3136
	v_mul_f32_e32 v2, v39, v80
	v_cvt_pk_bf16_f32 v2, v2, s0
	global_store_short v[0:1], v2, off offset:3200
	v_mul_f32_e32 v2, v55, v80
	v_cvt_pk_bf16_f32 v2, v2, s0
	global_store_short v[0:1], v2, off offset:3264
	v_mul_f32_e32 v0, v8, v72
	v_cvt_pk_bf16_f32 v2, v0, s0
	v_add_co_u32_e32 v0, vcc, s48, v64
	v_rcp_f32_e32 v69, v69
	s_nop 0
	v_addc_co_u32_e32 v1, vcc, 0, v65, vcc
	global_store_short v[0:1], v2, off
	v_mul_f32_e32 v2, v24, v72
	v_cvt_pk_bf16_f32 v2, v2, s0
	global_store_short v[0:1], v2, off offset:64
	v_mul_f32_e32 v2, v40, v72
	v_cvt_pk_bf16_f32 v2, v2, s0
	global_store_short v[0:1], v2, off offset:128
	v_mul_f32_e32 v2, v56, v72
	v_cvt_pk_bf16_f32 v2, v2, s0
	global_store_short v[0:1], v2, off offset:192
	v_mul_f32_e32 v2, v9, v81
	v_cvt_pk_bf16_f32 v2, v2, s0
	global_store_short v[0:1], v2, off offset:1024
	v_mul_f32_e32 v2, v25, v81
	v_cvt_pk_bf16_f32 v2, v2, s0
	global_store_short v[0:1], v2, off offset:1088
	v_mul_f32_e32 v2, v41, v81
	v_cvt_pk_bf16_f32 v2, v2, s0
	global_store_short v[0:1], v2, off offset:1152
	v_mul_f32_e32 v2, v57, v81
	v_cvt_pk_bf16_f32 v2, v2, s0
	global_store_short v[0:1], v2, off offset:1216
	v_mul_f32_e32 v2, v10, v82
	v_cvt_pk_bf16_f32 v2, v2, s0
	global_store_short v[0:1], v2, off offset:2048
	v_mul_f32_e32 v2, v26, v82
	v_cvt_pk_bf16_f32 v2, v2, s0
	global_store_short v[0:1], v2, off offset:2112
	v_mul_f32_e32 v2, v42, v82
	v_cvt_pk_bf16_f32 v2, v2, s0
	global_store_short v[0:1], v2, off offset:2176
	v_mul_f32_e32 v2, v58, v82
	v_cvt_pk_bf16_f32 v2, v2, s0
	global_store_short v[0:1], v2, off offset:2240
	v_mul_f32_e32 v2, v11, v83
	v_cvt_pk_bf16_f32 v2, v2, s0
	global_store_short v[0:1], v2, off offset:3072
	v_mul_f32_e32 v2, v27, v83
	v_cvt_pk_bf16_f32 v2, v2, s0
	global_store_short v[0:1], v2, off offset:3136
	v_mul_f32_e32 v2, v43, v83
	v_cvt_pk_bf16_f32 v2, v2, s0
	global_store_short v[0:1], v2, off offset:3200
	v_mul_f32_e32 v2, v59, v83
	v_cvt_pk_bf16_f32 v2, v2, s0
	global_store_short v[0:1], v2, off offset:3264
	v_mul_f32_e32 v0, v12, v68
	v_cvt_pk_bf16_f32 v2, v0, s0
	v_add_co_u32_e32 v0, vcc, s49, v64
	v_rcp_f32_e32 v70, v70
	s_nop 0
	v_addc_co_u32_e32 v1, vcc, 0, v65, vcc
	global_store_short v[0:1], v2, off
	v_mul_f32_e32 v2, v28, v68
	v_cvt_pk_bf16_f32 v2, v2, s0
	global_store_short v[0:1], v2, off offset:64
	v_mul_f32_e32 v2, v44, v68
	v_cvt_pk_bf16_f32 v2, v2, s0
	global_store_short v[0:1], v2, off offset:128
	v_mul_f32_e32 v2, v60, v68
	v_cvt_pk_bf16_f32 v2, v2, s0
	global_store_short v[0:1], v2, off offset:192
	v_mul_f32_e32 v2, v13, v69
	v_cvt_pk_bf16_f32 v2, v2, s0
	global_store_short v[0:1], v2, off offset:1024
	v_mul_f32_e32 v2, v29, v69
	v_cvt_pk_bf16_f32 v2, v2, s0
	global_store_short v[0:1], v2, off offset:1088
	v_mul_f32_e32 v2, v45, v69
	v_cvt_pk_bf16_f32 v2, v2, s0
	global_store_short v[0:1], v2, off offset:1152
	v_mul_f32_e32 v2, v61, v69
	v_cvt_pk_bf16_f32 v2, v2, s0
	global_store_short v[0:1], v2, off offset:1216
	v_mul_f32_e32 v2, v14, v70
	v_cvt_pk_bf16_f32 v2, v2, s0
	global_store_short v[0:1], v2, off offset:2048
	v_mul_f32_e32 v2, v30, v70
	v_cvt_pk_bf16_f32 v2, v2, s0
	v_rcp_f32_e32 v71, v71
	global_store_short v[0:1], v2, off offset:2112
	v_mul_f32_e32 v2, v46, v70
	v_cvt_pk_bf16_f32 v2, v2, s0
	global_store_short v[0:1], v2, off offset:2176
	v_mul_f32_e32 v2, v62, v70
	v_cvt_pk_bf16_f32 v2, v2, s0
	global_store_short v[0:1], v2, off offset:2240
	v_mul_f32_e32 v2, v15, v71
	v_cvt_pk_bf16_f32 v2, v2, s0
	global_store_short v[0:1], v2, off offset:3072
	v_mul_f32_e32 v2, v31, v71
	v_cvt_pk_bf16_f32 v2, v2, s0
	global_store_short v[0:1], v2, off offset:3136
	v_mul_f32_e32 v2, v47, v71
	v_cvt_pk_bf16_f32 v2, v2, s0
	global_store_short v[0:1], v2, off offset:3200
	v_mul_f32_e32 v2, v63, v71
	s_add_i32 s70, s70, 1
	s_add_i32 s34, s34, s35
	v_cvt_pk_bf16_f32 v2, v2, s0
	s_bitcmp1_b32 s70, 0
	global_store_short v[0:1], v2, off offset:3264
	s_waitcnt vmcnt(63) expcnt(7) lgkmcnt(15)
	s_barrier
	s_cbranch_scc0 .LBB0_859
